# P6 unit order remapped so every workgroup gets one unit of each output segment (balances the slow chunk-transposed store epilogue)
# speedup vs baseline: 1.0307x; 1.0006x over previous
; DI float ssq8(const float* p) { const f32x4 a = *(const f32x4*)p, b = *(const f32x4*)(p + 4); return ((a[0] + a[1]) + (a[2] + a[3])) + ((b[0] + b[1]) + (b[2] + b[3])); }
;     __host__ __device__ bool next(int i, Unit& u) const {
;         const long L = (long)i * G + c; if (L >= nwg) return false;
;         int wgid = (int)L; { const int q = nwg / NXCD, r = nwg % NXCD, xcd = wgid % NXCD, off = wgid / NXCD; wgid = (xcd < r ? xcd * (q + 1) : r * (q + 1) + (xcd - r) * q) + off; }
;         const int nig = WGM * nN, gid = wgid / nig, fm = gid * WGM, gsz = (nM - fm) < WGM ? (nM - fm) : WGM;
;         u.pm = fm + ((wgid % nig) % gsz); u.pn = (wgid % nig) / gsz; return true;
;     DI void operator()(const f32x4 (&acc)[2][2][4][2], const Unit& u, int wr, int wc, int fr, int fq) const {
;     ...
;         const int rbase = u.pm * 256 + wr * 64 + fr;
;         float rsv[8];
; #pragma unroll
;         for (int i = 0; i < 8; ++i) rsv[i] = ssq8(ssq + (size_t)(rbase + (i >> 2) * 128 + (i & 3) * 16) * 32 + 8 * fq);
; #pragma unroll
;         for (int i = 0; i < 8; ++i) { float sq = rsv[i]; sq += __shfl_xor(sq, 16); sq += __shfl_xor(sq, 32); rsv[i] = rsqrtf(sq * (1.f / 2048.f) + EPS_); }
.LBB0_783:
	s_andn2_b64 vcc, exec, s[4:5]
	s_cbranch_vccnz .LBB0_931
	s_and_b32 s6, s2, 7
	s_lshr_b32 s6, s6, 1
	s_lshl_b32 s6, s6, 3
	s_bfe_u32 s8, s2, 0x30003
	s_add_i32 s6, s6, s8
	s_and_b32 s8, s2, 1
	s_lshl_b32 s8, s8, 2
	s_lshr_b32 s9, s2, 6
	s_add_i32 s8, s8, s9
	v_cmp_gt_u32_e32 vcc, 0x100, v253
	s_and_saveexec_b64 s[98:99], vcc
	s_cbranch_execz .Lrt6_skip
	s_lshl_b32 s100, s6, 15
	s_add_u32 s100, s100, s82
	s_addc_u32 s101, s83, 0
	s_add_u32 s100, s100, 0x100000
	s_addc_u32 s101, s101, 0
	v_lshlrev_b32_e32 v0, 7, v253
	global_load_dwordx4 v[4:7], v0, s[100:101]
	global_load_dwordx4 v[8:11], v0, s[100:101] offset:16
	global_load_dwordx4 v[12:15], v0, s[100:101] offset:32
	global_load_dwordx4 v[16:19], v0, s[100:101] offset:48
	global_load_dwordx4 v[20:23], v0, s[100:101] offset:64
	global_load_dwordx4 v[24:27], v0, s[100:101] offset:80
	global_load_dwordx4 v[28:31], v0, s[100:101] offset:96
	global_load_dwordx4 v[32:35], v0, s[100:101] offset:112
	s_waitcnt vmcnt(0)
	v_add_f32_e32 v36, v4, v5
	v_add_f32_e32 v37, v6, v7
	v_add_f32_e32 v36, v36, v37
	v_add_f32_e32 v37, v8, v9
	v_add_f32_e32 v38, v10, v11
	v_add_f32_e32 v37, v37, v38
	v_add_f32_e32 v40, v36, v37
	v_add_f32_e32 v36, v12, v13
	v_add_f32_e32 v37, v14, v15
	v_add_f32_e32 v36, v36, v37
	v_add_f32_e32 v37, v16, v17
	v_add_f32_e32 v38, v18, v19
	v_add_f32_e32 v37, v37, v38
	v_add_f32_e32 v41, v36, v37
	v_add_f32_e32 v36, v20, v21
	v_add_f32_e32 v37, v22, v23
	v_add_f32_e32 v36, v36, v37
	v_add_f32_e32 v37, v24, v25
	v_add_f32_e32 v38, v26, v27
	v_add_f32_e32 v37, v37, v38
	v_add_f32_e32 v42, v36, v37
	v_add_f32_e32 v36, v28, v29
	v_add_f32_e32 v37, v30, v31
	v_add_f32_e32 v36, v36, v37
	v_add_f32_e32 v37, v32, v33
	v_add_f32_e32 v38, v34, v35
	v_add_f32_e32 v37, v37, v38
	v_add_f32_e32 v43, v36, v37
	v_add_f32_e32 v36, v40, v41
	v_add_f32_e32 v37, v42, v43
	v_add_f32_e32 v36, v36, v37
	v_lshlrev_b32_e32 v1, 2, v253
	v_add_u32_e32 v1, 0x20400, v1
	ds_write_b32 v1, v36

; template <class Epi, class Sched>
; __device__ __forceinline__ void gemm_phase(LAS unsigned char* lds, const Gemm g, const Sched& S, const Epi& E) {
;     ...
;         const bool has_next = S.next(ui + 1, nxt);
;         const char* nA = has_next ? (const char*)g.A + (size_t)nxt.pm * tsA : cA; const char* nB = has_next ? (const char*)g.Bt + (size_t)nxt.pn * tsB : cB;
;     ...
; #pragma unroll
;         for (int a = 0; a < 2; ++a)
; #pragma unroll
;             for (int b = 0; b < 2; ++b)
; #pragma unroll
;                 for (int m = 0; m < 4; ++m)
; #pragma unroll
;                     for (int n = 0; n < 2; ++n) acc[a][b][m][n] = (f32x4){0.f, 0.f, 0.f, 0.f};
;         cur = nxt; cA = nA; cB = nB; ++ui;
.LBB0_795:
	s_and_b32 s34, s2, 7
	s_lshr_b32 s34, s34, 1
	s_lshl_b32 s34, s34, 3
	s_bfe_u32 s7, s2, 0x30003
	s_add_i32 s34, s34, s7
	s_lshl_b32 s30, s52, 3
	s_and_b32 s7, s2, 1
	s_lshl_b32 s7, s7, 2
	s_add_i32 s30, s30, s7
	s_lshr_b32 s7, s2, 6
	s_add_i32 s30, s30, s7
	s_ashr_i32 s35, s34, 31
	s_lshl_b64 s[36:37], s[34:35], 20
	s_add_u32 s36, s62, s36
	s_addc_u32 s37, s63, s37
	s_and_b64 s[38:39], s[4:5], exec
	s_cselect_b32 s7, s37, s11
	s_cselect_b32 s9, s36, s10
	s_ashr_i32 s31, s30, 31
	s_lshl_b64 s[38:39], s[30:31], 20
	s_add_u32 s38, s3, s38
	s_addc_u32 s39, s46, s39
	s_and_b64 s[42:43], s[4:5], exec
	s_cselect_b32 s31, s39, s41
	s_cselect_b32 s35, s38, s40
	s_add_u32 s10, s10, 0x80080
	s_addc_u32 s11, s11, 0
	s_add_u32 s44, s40, 0x100
	v_mov_b32_e32 v0, 0
	s_addc_u32 s45, s41, 0
	s_mov_b32 s69, -2
	v_mov_b32_e32 v1, v0
	v_mov_b32_e32 v2, v0
	v_mov_b32_e32 v3, v0
	v_mov_b32_e32 v4, v0
	v_mov_b32_e32 v5, v0
	v_mov_b32_e32 v6, v0
	v_mov_b32_e32 v7, v0
	v_mov_b32_e32 v16, v0
	v_mov_b32_e32 v17, v0
	v_mov_b32_e32 v18, v0
	v_mov_b32_e32 v19, v0
	v_mov_b32_e32 v20, v0
	v_mov_b32_e32 v21, v0
	v_mov_b32_e32 v22, v0
	v_mov_b32_e32 v23, v0
	v_mov_b32_e32 v32, v0
	v_mov_b32_e32 v33, v0
	v_mov_b32_e32 v34, v0
	v_mov_b32_e32 v35, v0
	v_mov_b32_e32 v36, v0
	v_mov_b32_e32 v37, v0
	v_mov_b32_e32 v38, v0
	v_mov_b32_e32 v39, v0
	v_mov_b32_e32 v48, v0
	v_mov_b32_e32 v49, v0
	v_mov_b32_e32 v50, v0
	v_mov_b32_e32 v51, v0
	v_mov_b32_e32 v52, v0
	v_mov_b32_e32 v53, v0
	v_mov_b32_e32 v54, v0
	v_mov_b32_e32 v55, v0
	v_mov_b32_e32 v8, v0
	v_mov_b32_e32 v9, v0
	v_mov_b32_e32 v10, v0
	v_mov_b32_e32 v11, v0
	v_mov_b32_e32 v12, v0
	v_mov_b32_e32 v13, v0
	v_mov_b32_e32 v14, v0
	v_mov_b32_e32 v15, v0
	v_mov_b32_e32 v24, v0
	v_mov_b32_e32 v25, v0
	v_mov_b32_e32 v26, v0
	v_mov_b32_e32 v27, v0
	v_mov_b32_e32 v28, v0
	v_mov_b32_e32 v29, v0
	v_mov_b32_e32 v30, v0
	v_mov_b32_e32 v31, v0
	v_mov_b32_e32 v40, v0
	v_mov_b32_e32 v41, v0
	v_mov_b32_e32 v42, v0
	v_mov_b32_e32 v43, v0
	v_mov_b32_e32 v44, v0
	v_mov_b32_e32 v45, v0
	v_mov_b32_e32 v46, v0
	v_mov_b32_e32 v47, v0
	v_mov_b32_e32 v56, v0
	v_mov_b32_e32 v57, v0
	v_mov_b32_e32 v58, v0
	v_mov_b32_e32 v59, v0
	v_mov_b32_e32 v60, v0
	v_mov_b32_e32 v61, v0
	v_mov_b32_e32 v62, v0
	v_mov_b32_e32 v63, v0
	v_mov_b32_e32 v64, v0
	v_mov_b32_e32 v65, v0
	v_mov_b32_e32 v66, v0
	v_mov_b32_e32 v67, v0
	v_mov_b32_e32 v68, v0
	v_mov_b32_e32 v69, v0
	v_mov_b32_e32 v70, v0
	v_mov_b32_e32 v71, v0
	v_mov_b32_e32 v80, v0
	v_mov_b32_e32 v81, v0
	v_mov_b32_e32 v82, v0
	v_mov_b32_e32 v83, v0
	v_mov_b32_e32 v84, v0
	v_mov_b32_e32 v85, v0
	v_mov_b32_e32 v86, v0
	v_mov_b32_e32 v87, v0
	v_mov_b32_e32 v96, v0
	v_mov_b32_e32 v97, v0
	v_mov_b32_e32 v98, v0
	v_mov_b32_e32 v99, v0
	v_mov_b32_e32 v100, v0
	v_mov_b32_e32 v101, v0
	v_mov_b32_e32 v102, v0
	v_mov_b32_e32 v103, v0
	v_mov_b32_e32 v112, v0
	v_mov_b32_e32 v113, v0
	v_mov_b32_e32 v114, v0
	v_mov_b32_e32 v115, v0
	v_mov_b32_e32 v116, v0
	v_mov_b32_e32 v117, v0
	v_mov_b32_e32 v118, v0
	v_mov_b32_e32 v119, v0
	v_mov_b32_e32 v72, v0
	v_mov_b32_e32 v73, v0
	v_mov_b32_e32 v74, v0
	v_mov_b32_e32 v75, v0
	v_mov_b32_e32 v76, v0
	v_mov_b32_e32 v77, v0
	v_mov_b32_e32 v78, v0
	v_mov_b32_e32 v79, v0
	v_mov_b32_e32 v88, v0
	v_mov_b32_e32 v89, v0
	v_mov_b32_e32 v90, v0
	v_mov_b32_e32 v91, v0
	v_mov_b32_e32 v92, v0
	v_mov_b32_e32 v93, v0
	v_mov_b32_e32 v94, v0
	v_mov_b32_e32 v95, v0
	v_mov_b32_e32 v104, v0
	v_mov_b32_e32 v105, v0
	v_mov_b32_e32 v106, v0
	v_mov_b32_e32 v107, v0
	v_mov_b32_e32 v108, v0
	v_mov_b32_e32 v109, v0
	v_mov_b32_e32 v110, v0
	v_mov_b32_e32 v111, v0
	v_mov_b32_e32 v120, v0
	v_mov_b32_e32 v121, v0
	v_mov_b32_e32 v122, v0
	v_mov_b32_e32 v123, v0
	v_mov_b32_e32 v124, v0
	v_mov_b32_e32 v125, v0
	v_mov_b32_e32 v126, v0
	v_mov_b32_e32 v127, v0

; DI void hgA_load(unsigned char* ws, int item, unsigned (&lf)[16], u32x4 (&ivw)[2]) {
;     const int tid = threadIdx.x, b = item >> 10, h = (item >> 6) & 15, c = item & 63, t0 = b * SEQ + c * 64, k = tid & 127, tq = tid >> 7;
;     const bf16_t* LOGF = (const bf16_t*)(ws + WS_LOGF);
; #pragma unroll
;     for (int i = 0; i < 16; ++i) lf[i] = LOGF[(size_t)(t0 + tq * 16 + i) * DM + h * 128 + k];
;     hg_iv_load((const bf16_t*)(ws + WS_IV), item, ivw);
; DI void hgA_item(LAS unsigned char* lds, unsigned char* ws, unsigned char* ob, int item, const unsigned (&lfr)[16], const u32x4 (&ivw)[2], const float* lbp) {
;     ...
;     { const float lbk = lbp[h * 128 + (tid & 127)];
.LBB0_989:
	s_add_i32 s36, s37, s58
	s_cmpk_gt_i32 s36, 0x7ff
	s_cselect_b64 s[16:17], -1, 0
	s_and_b64 vcc, exec, s[16:17]
	v_mov_b32_e32 v59, 0
	v_mov_b32_e32 v60, 0
	v_mov_b32_e32 v61, 0
	v_mov_b32_e32 v62, 0
	v_mov_b32_e32 v63, 0
	v_mov_b32_e32 v64, 0
	v_mov_b32_e32 v65, 0
	v_mov_b32_e32 v66, 0
	v_mov_b32_e32 v67, 0
	v_mov_b32_e32 v68, 0
	v_mov_b32_e32 v69, 0
	v_mov_b32_e32 v70, 0
	v_mov_b32_e32 v71, 0
	v_mov_b32_e32 v72, 0
	v_mov_b32_e32 v73, 0
	v_mov_b32_e32 v74, 0
	s_bfe_u32 s18, s37, 0x40006
	v_lshlrev_b32_e32 v100, 2, v45
	v_lshl_or_b32 v100, s18, 9, v100
	global_load_dword v100, v100, s[24:25]
	s_cbranch_vccnz .LBB0_991
	s_and_b32 s10, s23, 0xfffff000
	s_and_b32 s18, s27, 0xfc0
	s_or_b32 s10, s10, s18
	v_add_u32_e32 v24, s10, v47
	s_and_b32 s10, s29, 0x780
	v_or_b32_e32 v60, 6, v24
	s_lshl_b32 s10, s10, 1
	v_ashrrev_i32_e32 v61, 31, v60
	v_lshl_add_u64 v[26:27], v[42:43], 0, s[10:11]
	v_lshlrev_b64 v[60:61], 12, v[60:61]
	v_lshl_add_u64 v[66:67], v[26:27], 0, v[60:61]
	v_or_b32_e32 v60, 7, v24
	v_ashrrev_i32_e32 v25, 31, v24
	v_or_b32_e32 v30, 1, v24
	v_or_b32_e32 v32, 2, v24
	v_or_b32_e32 v34, 3, v24
	v_or_b32_e32 v36, 4, v24
	v_or_b32_e32 v38, 5, v24
	v_ashrrev_i32_e32 v61, 31, v60
	v_lshlrev_b64 v[28:29], 12, v[24:25]
	v_ashrrev_i32_e32 v31, 31, v30
	v_ashrrev_i32_e32 v33, 31, v32
	v_ashrrev_i32_e32 v35, 31, v34
	v_ashrrev_i32_e32 v37, 31, v36
	v_ashrrev_i32_e32 v39, 31, v38
	v_lshlrev_b64 v[60:61], 12, v[60:61]
	v_lshl_add_u64 v[28:29], v[26:27], 0, v[28:29]
	v_lshlrev_b64 v[30:31], 12, v[30:31]
	v_lshlrev_b64 v[32:33], 12, v[32:33]
	v_lshlrev_b64 v[34:35], 12, v[34:35]
	v_lshlrev_b64 v[36:37], 12, v[36:37]
	v_lshlrev_b64 v[38:39], 12, v[38:39]
	v_lshl_add_u64 v[68:69], v[26:27], 0, v[60:61]
	v_lshl_add_u64 v[30:31], v[26:27], 0, v[30:31]
	v_lshl_add_u64 v[32:33], v[26:27], 0, v[32:33]
	v_lshl_add_u64 v[34:35], v[26:27], 0, v[34:35]
	v_lshl_add_u64 v[36:37], v[26:27], 0, v[36:37]
	v_lshl_add_u64 v[38:39], v[26:27], 0, v[38:39]
	global_load_ushort v59, v[28:29], off
	global_load_ushort v60, v[30:31], off
	global_load_ushort v61, v[32:33], off
	global_load_ushort v62, v[34:35], off
	global_load_ushort v63, v[36:37], off
	global_load_ushort v64, v[38:39], off
	global_load_ushort v65, v[66:67], off
	s_nop 0
	global_load_ushort v66, v[68:69], off
	v_or_b32_e32 v28, 8, v24
	v_or_b32_e32 v68, 14, v24
	v_ashrrev_i32_e32 v29, 31, v28
	v_or_b32_e32 v30, 9, v24
	v_or_b32_e32 v32, 10, v24
	v_or_b32_e32 v34, 11, v24
	v_or_b32_e32 v36, 12, v24
	v_or_b32_e32 v38, 13, v24
	v_ashrrev_i32_e32 v69, 31, v68
	v_or_b32_e32 v24, 15, v24
	v_lshlrev_b64 v[28:29], 12, v[28:29]
	v_ashrrev_i32_e32 v31, 31, v30
	v_ashrrev_i32_e32 v33, 31, v32
	v_ashrrev_i32_e32 v35, 31, v34
	v_ashrrev_i32_e32 v37, 31, v36
	v_ashrrev_i32_e32 v39, 31, v38
	v_lshlrev_b64 v[68:69], 12, v[68:69]
	v_ashrrev_i32_e32 v25, 31, v24
	v_lshl_add_u64 v[28:29], v[26:27], 0, v[28:29]
	v_lshlrev_b64 v[30:31], 12, v[30:31]
	v_lshlrev_b64 v[32:33], 12, v[32:33]
	v_lshlrev_b64 v[34:35], 12, v[34:35]
	v_lshlrev_b64 v[36:37], 12, v[36:37]
	v_lshlrev_b64 v[38:39], 12, v[38:39]
	v_lshl_add_u64 v[74:75], v[26:27], 0, v[68:69]
	v_lshlrev_b64 v[24:25], 12, v[24:25]
	v_lshl_add_u64 v[30:31], v[26:27], 0, v[30:31]
	v_lshl_add_u64 v[32:33], v[26:27], 0, v[32:33]
	v_lshl_add_u64 v[34:35], v[26:27], 0, v[34:35]
	v_lshl_add_u64 v[36:37], v[26:27], 0, v[36:37]
	v_lshl_add_u64 v[38:39], v[26:27], 0, v[38:39]
	v_lshl_add_u64 v[24:25], v[26:27], 0, v[24:25]
	global_load_ushort v67, v[28:29], off
	global_load_ushort v68, v[30:31], off
	global_load_ushort v69, v[32:33], off
	global_load_ushort v70, v[34:35], off
	global_load_ushort v71, v[36:37], off
	global_load_ushort v72, v[38:39], off
	global_load_ushort v73, v[74:75], off
	s_nop 0
	global_load_ushort v74, v[24:25], off
	v_add_co_u32_e32 v24, vcc, 0xffffe000, v48
	s_nop 1
	v_addc_co_u32_e32 v25, vcc, -1, v49, vcc
	global_load_dwordx4 v[36:39], v[24:25], off
	global_load_dwordx4 v[32:35], v[48:49], off

; DI bf16_t* ds_item_ptr(unsigned char* ws, unsigned char* ob, int b, int h, int c) { return (bf16_t*)(b == 0 ? ws + WS_DS0 : ob) + ((size_t)(h * 64 + c)) * 16384; }
; DI void hgC_load(unsigned char* ws, int item, unsigned (&lf)[16], unsigned (&qv)[16], u32x4 (&ivw)[2]) {
;     const int tid = threadIdx.x, b = item >> 10, h = (item >> 6) & 15, c = item & 63, t0 = b * SEQ + c * 64, kp = tid & 63, tq = tid >> 6;
;     const bf16_t* LOGF = (const bf16_t*)(ws + WS_LOGF);
;     const bf16_t* Q2 = (const bf16_t*)(ws + WS_Q2);
; #pragma unroll
;     for (int i = 0; i < 8; ++i) { const size_t o = (size_t)(t0 + tq * 8 + i) * DM + h * 128 + 2 * kp; lf[i] = *(const unsigned*)(LOGF + o); qv[i] = *(const unsigned*)(Q2 + o); }
;     hg_iv_load((const bf16_t*)(ws + WS_IV), item, ivw);
; DI void hgC_item(LAS unsigned char* lds, unsigned char* ws, unsigned char* ob, int item, const float* ng, int dummy, const unsigned (&lfr)[16], const unsigned (&qvr)[16], const u32x4 (&ivw)[2], const float* lbp) {
;     ...
;     { const bf16_t* Sg = ds_item_ptr(ws, ob, b, h, c);
; #pragma unroll
;       for (int j = 0; j < 4; ++j) sreg[j] = *(const u32x4*)(Sg + (size_t)(tid + 512 * j) * 8);
; #pragma unroll
;       for (int j = 0; j < 2; ++j) { const int id = tid + 512 * j; gz[j] = *(const u32x4*)(G2 + (size_t)(t0 + (id >> 4)) * DM + h * 128 + (id & 15) * 8); } }
.LBB0_1116:
	s_and_b32 s56, s68, 63
	s_lshl_b32 s57, s56, 6
	s_bfe_u32 s91, s68, 0x40006
	s_or_b32 s33, s90, s57
	s_and_b32 s75, s97, 3
	s_cmpk_lt_u32 s68, 0x400
	s_cselect_b32 s57, s95, s81
	s_cselect_b32 s68, s94, s80
	s_lshl_b32 s56, s56, 15
	s_lshl_b32 s90, s91, 21
	s_or_b32 s56, s90, s56
	s_add_u32 s56, s68, s56
	s_addc_u32 s57, s57, 0
	v_lshl_add_u64 v[20:21], s[56:57], 0, v[80:81]
	v_add_co_u32_e32 v12, vcc, s3, v20
	global_load_dwordx4 v[8:11], v80, s[56:57]
	s_nop 0
	v_addc_co_u32_e32 v13, vcc, 0, v21, vcc
	s_movk_i32 s56, 0x4000
	v_add_co_u32_e32 v16, vcc, s56, v20
	v_or_b32_e32 v42, s33, v101
	v_add_u32_e32 v44, s33, v102
	v_addc_co_u32_e32 v17, vcc, 0, v21, vcc
	s_movk_i32 s56, 0x6000
	s_lshl_b32 s68, s91, 8
	v_ashrrev_i32_e32 v43, 31, v42
	v_ashrrev_i32_e32 v45, 31, v44
	v_add_co_u32_e32 v20, vcc, s56, v20
	v_lshl_add_u64 v[40:41], v[84:85], 0, s[68:69]
	v_lshlrev_b64 v[96:97], 12, v[42:43]
	v_lshlrev_b64 v[94:95], 12, v[44:45]
	s_lshl_b32 s68, s91, 9
	v_addc_co_u32_e32 v21, vcc, 0, v21, vcc
	v_lshl_add_u64 v[42:43], v[40:41], 0, v[96:97]
	v_lshl_add_u64 v[40:41], v[40:41], 0, v[94:95]
	v_cvt_f32_f16_e32 v54, v48
	v_cvt_f32_f16_sdwa v55, v48 dst_sel:DWORD dst_unused:UNUSED_PAD src0_sel:WORD_1
	v_lshl_add_u64 v[48:49], v[86:87], 0, s[68:69]
	global_load_dwordx4 v[12:15], v[12:13], off
	s_nop 0
	global_load_dwordx4 v[16:19], v[16:17], off
	v_mul_f32_e32 v54, 0x3fb8aa3b, v54
	global_load_dwordx4 v[20:23], v[20:21], off
	s_nop 0
	global_load_dwordx4 v[44:47], v[42:43], off
	s_nop 0
	global_load_dwordx4 v[40:43], v[40:41], off
	v_exp_f32_e32 v54, v54
	global_load_dwordx2 v[58:59], v[48:49], off
	s_and_b64 vcc, exec, s[76:77]
	s_cbranch_vccnz .LBB0_1114
	s_lshl_b32 s56, s74, 2
	s_lshl_b32 s57, s74, 6
	s_and_b32 s56, s56, 0xfffff000
	s_and_b32 s57, s57, 0xfc0
	s_or_b32 s56, s56, s57
	v_add_u32_e32 v148, s56, v89
	s_lshl_b32 s56, s74, 1
	s_and_b32 s56, s56, 0x780
	v_or_b32_e32 v152, s56, v98
	v_ashrrev_i32_e32 v149, 31, v148
	v_or_b32_e32 v154, 1, v148
	v_or_b32_e32 v158, 2, v148
	v_or_b32_e32 v162, 3, v148
	v_lshlrev_b64 v[150:151], 12, v[148:149]
	v_lshlrev_b32_e32 v34, 1, v152
	v_ashrrev_i32_e32 v155, 31, v154
	v_ashrrev_i32_e32 v159, 31, v158
	v_ashrrev_i32_e32 v163, 31, v162
	v_or_b32_e32 v150, v150, v34
	v_lshlrev_b64 v[154:155], 12, v[154:155]
	v_lshlrev_b64 v[158:159], 12, v[158:159]
	v_lshlrev_b64 v[162:163], 12, v[162:163]
	v_lshl_add_u64 v[152:153], s[64:65], 0, v[150:151]
	v_lshl_add_u64 v[150:151], s[66:67], 0, v[150:151]
	v_or_b32_e32 v154, v154, v34
	v_or_b32_e32 v158, v158, v34
	v_or_b32_e32 v162, v162, v34
	v_lshl_add_u64 v[156:157], s[64:65], 0, v[154:155]
	v_lshl_add_u64 v[154:155], s[66:67], 0, v[154:155]
	v_lshl_add_u64 v[160:161], s[64:65], 0, v[158:159]
	v_lshl_add_u64 v[158:159], s[66:67], 0, v[158:159]
	v_lshl_add_u64 v[32:33], s[64:65], 0, v[162:163]
	v_lshl_add_u64 v[162:163], s[66:67], 0, v[162:163]
	global_load_dword v120, v[152:153], off
	global_load_dword v121, v[150:151], off
	global_load_dword v122, v[156:157], off
	global_load_dword v123, v[154:155], off
	global_load_dword v124, v[160:161], off
	global_load_dword v125, v[158:159], off
	global_load_dword v126, v[32:33], off
	global_load_dword v127, v[162:163], off
	v_or_b32_e32 v150, 4, v148
	v_ashrrev_i32_e32 v151, 31, v150
	v_or_b32_e32 v154, 5, v148
	v_or_b32_e32 v158, 6, v148
	v_or_b32_e32 v148, 7, v148
	v_lshlrev_b64 v[150:151], 12, v[150:151]
	v_ashrrev_i32_e32 v155, 31, v154
	v_ashrrev_i32_e32 v159, 31, v158
	v_ashrrev_i32_e32 v149, 31, v148
	v_or_b32_e32 v150, v150, v34
	v_lshlrev_b64 v[154:155], 12, v[154:155]
	v_lshlrev_b64 v[158:159], 12, v[158:159]
	v_lshlrev_b64 v[148:149], 12, v[148:149]
	v_lshl_add_u64 v[152:153], s[64:65], 0, v[150:151]
	v_or_b32_e32 v154, v154, v34
	v_or_b32_e32 v158, v158, v34
	v_or_b32_e32 v148, v148, v34
	v_lshl_add_u64 v[150:151], s[66:67], 0, v[150:151]
	v_lshl_add_u64 v[156:157], s[64:65], 0, v[154:155]
	v_lshl_add_u64 v[154:155], s[66:67], 0, v[154:155]
	v_lshl_add_u64 v[160:161], s[64:65], 0, v[158:159]
	v_lshl_add_u64 v[158:159], s[66:67], 0, v[158:159]
	v_lshl_add_u64 v[162:163], s[64:65], 0, v[148:149]
	v_lshl_add_u64 v[148:149], s[66:67], 0, v[148:149]
	global_load_dword v128, v[152:153], off
	global_load_dword v129, v[150:151], off
	global_load_dword v130, v[156:157], off
	global_load_dword v131, v[154:155], off
	global_load_dword v132, v[160:161], off
	global_load_dword v133, v[158:159], off
	global_load_dword v134, v[162:163], off
	global_load_dword v135, v[148:149], off
	s_mov_b32 s56, s74
	s_ashr_i32 s57, s74, 31
	s_lshl_b64 s[56:57], s[56:57], 14
	v_lshl_add_u64 v[148:149], v[82:83], 0, s[56:57]
	v_add_co_u32_e32 v150, vcc, 0x2000, v148
	s_nop 1
	v_addc_co_u32_e32 v151, vcc, 0, v149, vcc
	global_load_dwordx4 v[32:35], v[148:149], off
	global_load_dwordx4 v[36:39], v[150:151], off
